# hazard clean-up of the batched small GEMMs: MFMA-result to LDS-store distance 12 (was 11), two wait states between v_add_co and v_addc in three address computations; no other change
# speedup vs baseline: 1.0245x; 1.0021x over previous
; template <int MODE> __device__ __forceinline__ void small_gemm_res(LAS unsigned char* lds, const bf16* A, const bf16* Bt, int K, const float* base, const bf16* baseb, float* H, bf16* XN, float* SS, float alpha, const bf16* GGs, int bx, int G, int tid) {
;     ...
;     for (int tile = bx; tile < 256; tile += G) {
;         const int t0 = (tile >> 4) * 32, n0 = (tile & 15) * 64;
;         f32x16 acc0, acc1;
; #pragma unroll
;         for (int r = 0; r < 16; ++r) { acc0[r] = 0.f; acc1[r] = 0.f; }
;         const bf16* ap = A + (size_t)(t0 + r32) * K + w * kw + 8 * hi;
;         const bf16* b0p = Bt + (size_t)(n0 + r32) * K + w * kw + 8 * hi; const bf16* b1p = b0p + (size_t)32 * K;
; #pragma unroll 4
;         for (int k = 0; k < kw; k += 16) {
;             const bf16x8 x = *(const bf16x8*)(ap + k), w0 = *(const bf16x8*)(b0p + k), w1 = *(const bf16x8*)(b1p + k);
;             acc0 = __builtin_amdgcn_mfma_f32_32x32x16_bf16(w0, x, acc0, 0, 0, 0); acc1 = __builtin_amdgcn_mfma_f32_32x32x16_bf16(w1, x, acc1, 0, 0, 0);
;         }
.LBB0_290:
	s_and_b32 s14, s1, 0x3c0
	v_or_b32_e32 v2, s14, v41
	v_mul_u32_u24_e32 v2, 0xb00, v2
	v_lshlrev_b32_e32 v34, 1, v2
	v_lshl_add_u64 v[86:87], v[38:39], 0, v[34:35]
	v_add_co_u32_e32 v90, vcc, 0x2c000, v86
	s_and_b32 s16, s3, 0xffffffe0
	v_or_b32_e32 v6, s16, v41
	v_mad_i64_i32 v[88:89], s[22:23], v6, s19, v[36:37]
	v_addc_co_u32_e32 v91, vcc, 0, v87, vcc
	global_load_dwordx4 v[72:75], v[86:87], off
	global_load_dwordx4 v[76:79], v[88:89], off
	global_load_dwordx4 v[80:83], v[90:91], off
	global_load_dwordx4 v[92:95], v[86:87], off offset:32
	global_load_dwordx4 v[96:99], v[88:89], off offset:32
	global_load_dwordx4 v[100:103], v[90:91], off offset:32
	global_load_dwordx4 v[104:107], v[86:87], off offset:64
	global_load_dwordx4 v[108:111], v[88:89], off offset:64
	global_load_dwordx4 v[112:115], v[90:91], off offset:64
	global_load_dwordx4 v[116:119], v[86:87], off offset:96
	global_load_dwordx4 v[120:123], v[88:89], off offset:96
	global_load_dwordx4 v[124:127], v[90:91], off offset:96
	global_load_dwordx4 v[208:211], v[86:87], off offset:128
	global_load_dwordx4 v[212:215], v[88:89], off offset:128
	global_load_dwordx4 v[216:219], v[90:91], off offset:128
	global_load_dwordx4 v[220:223], v[86:87], off offset:160
	global_load_dwordx4 v[224:227], v[88:89], off offset:160
	global_load_dwordx4 v[228:231], v[90:91], off offset:160
	global_load_dwordx4 v[232:235], v[86:87], off offset:192
	global_load_dwordx4 v[236:239], v[88:89], off offset:192
	global_load_dwordx4 v[166:169], v[90:91], off offset:192
	global_load_dwordx4 v[170:173], v[86:87], off offset:224
	global_load_dwordx4 v[174:177], v[88:89], off offset:224
	global_load_dwordx4 v[182:185], v[90:91], off offset:224
	global_load_dwordx4 v[186:189], v[86:87], off offset:256
	global_load_dwordx4 v[190:193], v[88:89], off offset:256
	global_load_dwordx4 v[240:243], v[90:91], off offset:256
	s_waitcnt vmcnt(24)
	v_mfma_f32_32x32x16_bf16 v[2:17], v[72:75], v[76:79], 0
	v_mfma_f32_32x32x16_bf16 v[18:33], v[80:83], v[76:79], 0
	global_load_dwordx4 v[72:75], v[86:87], off offset:288
	global_load_dwordx4 v[76:79], v[88:89], off offset:288
	global_load_dwordx4 v[80:83], v[90:91], off offset:288
	s_waitcnt vmcnt(24)
	v_mfma_f32_32x32x16_bf16 v[2:17], v[92:95], v[96:99], v[2:17]
	v_mfma_f32_32x32x16_bf16 v[18:33], v[100:103], v[96:99], v[18:33]
	global_load_dwordx4 v[92:95], v[86:87], off offset:320
	global_load_dwordx4 v[96:99], v[88:89], off offset:320
	global_load_dwordx4 v[100:103], v[90:91], off offset:320
	s_waitcnt vmcnt(24)
	v_mfma_f32_32x32x16_bf16 v[2:17], v[104:107], v[108:111], v[2:17]
	v_mfma_f32_32x32x16_bf16 v[18:33], v[112:115], v[108:111], v[18:33]
	global_load_dwordx4 v[104:107], v[86:87], off offset:352
	global_load_dwordx4 v[108:111], v[88:89], off offset:352
	global_load_dwordx4 v[112:115], v[90:91], off offset:352
	s_waitcnt vmcnt(24)
	v_mfma_f32_32x32x16_bf16 v[2:17], v[116:119], v[120:123], v[2:17]
	v_mfma_f32_32x32x16_bf16 v[18:33], v[124:127], v[120:123], v[18:33]
	global_load_dwordx4 v[116:119], v[86:87], off offset:384
	global_load_dwordx4 v[120:123], v[88:89], off offset:384
	global_load_dwordx4 v[124:127], v[90:91], off offset:384
	s_waitcnt vmcnt(24)
	v_mfma_f32_32x32x16_bf16 v[2:17], v[208:211], v[212:215], v[2:17]
	v_mfma_f32_32x32x16_bf16 v[18:33], v[216:219], v[212:215], v[18:33]
	global_load_dwordx4 v[208:211], v[86:87], off offset:416
	global_load_dwordx4 v[212:215], v[88:89], off offset:416
	global_load_dwordx4 v[216:219], v[90:91], off offset:416
	s_waitcnt vmcnt(24)
	v_mfma_f32_32x32x16_bf16 v[2:17], v[220:223], v[224:227], v[2:17]
	v_mfma_f32_32x32x16_bf16 v[18:33], v[228:231], v[224:227], v[18:33]
	global_load_dwordx4 v[220:223], v[86:87], off offset:448
	global_load_dwordx4 v[224:227], v[88:89], off offset:448
	global_load_dwordx4 v[228:231], v[90:91], off offset:448
	s_waitcnt vmcnt(24)
	v_mfma_f32_32x32x16_bf16 v[2:17], v[232:235], v[236:239], v[2:17]
	v_mfma_f32_32x32x16_bf16 v[18:33], v[166:169], v[236:239], v[18:33]
	global_load_dwordx4 v[232:235], v[86:87], off offset:480
	global_load_dwordx4 v[236:239], v[88:89], off offset:480
	global_load_dwordx4 v[166:169], v[90:91], off offset:480
	s_waitcnt vmcnt(24)
	v_mfma_f32_32x32x16_bf16 v[2:17], v[170:173], v[174:177], v[2:17]
	v_mfma_f32_32x32x16_bf16 v[18:33], v[182:185], v[174:177], v[18:33]
	global_load_dwordx4 v[170:173], v[86:87], off offset:512
	global_load_dwordx4 v[174:177], v[88:89], off offset:512
	global_load_dwordx4 v[182:185], v[90:91], off offset:512
	s_waitcnt vmcnt(24)
	v_mfma_f32_32x32x16_bf16 v[2:17], v[186:189], v[190:193], v[2:17]
	v_mfma_f32_32x32x16_bf16 v[18:33], v[240:243], v[190:193], v[18:33]
	global_load_dwordx4 v[186:189], v[86:87], off offset:544
	global_load_dwordx4 v[190:193], v[88:89], off offset:544
	global_load_dwordx4 v[240:243], v[90:91], off offset:544
	s_waitcnt vmcnt(24)
	v_mfma_f32_32x32x16_bf16 v[2:17], v[72:75], v[76:79], v[2:17]
	v_mfma_f32_32x32x16_bf16 v[18:33], v[80:83], v[76:79], v[18:33]
	global_load_dwordx4 v[72:75], v[86:87], off offset:576
	global_load_dwordx4 v[76:79], v[88:89], off offset:576
	global_load_dwordx4 v[80:83], v[90:91], off offset:576
	s_waitcnt vmcnt(24)
	v_mfma_f32_32x32x16_bf16 v[2:17], v[92:95], v[96:99], v[2:17]
	v_mfma_f32_32x32x16_bf16 v[18:33], v[100:103], v[96:99], v[18:33]
	global_load_dwordx4 v[92:95], v[86:87], off offset:608
	global_load_dwordx4 v[96:99], v[88:89], off offset:608
	global_load_dwordx4 v[100:103], v[90:91], off offset:608
	s_waitcnt vmcnt(24)
; #define LAS __attribute__((address_space(3)))
; __device__ __forceinline__ unsigned pk2(float lo, float hi) { return pg8::cvt_pk_bf16(lo, hi); }
; __device__ __forceinline__ float bflo(unsigned w) { return __uint_as_float(w << 16); }
; __device__ __forceinline__ float bfhi(unsigned w) { return __uint_as_float(w & 0xffff0000u); }
; __device__ __forceinline__ int crow(int r, int hi) { return (r & 3) + 8 * (r >> 2) + 4 * hi; }
; template <int MODE> __device__ __forceinline__ void small_gemm_res(LAS unsigned char* lds, const bf16* A, const bf16* Bt, int K, const float* base, const bf16* baseb, float* H, bf16* XN, float* SS, float alpha, const bf16* GGs, int bx, int G, int tid) {
;     ...
;         for (int k = 0; k < kw; k += 16) {
;             const bf16x8 x = *(const bf16x8*)(ap + k), w0 = *(const bf16x8*)(b0p + k), w1 = *(const bf16x8*)(b1p + k);
;             acc0 = __builtin_amdgcn_mfma_f32_32x32x16_bf16(w0, x, acc0, 0, 0, 0); acc1 = __builtin_amdgcn_mfma_f32_32x32x16_bf16(w1, x, acc1, 0, 0, 0);
;         }
;         LAS float* Pw = P + w * 2112;
; #pragma unroll
;         for (int r = 0; r < 16; ++r) { Pw[crow(r, hi) * 33 + r32] = acc0[r]; Pw[(32 + crow(r, hi)) * 33 + r32] = acc1[r]; }
;         __syncthreads();
;         const int tok = tid >> 4, nq = tid & 15;
;         float v[4] = {0.f, 0.f, 0.f, 0.f};
; #pragma unroll
;         for (int ww = 0; ww < 8; ++ww)
; #pragma unroll
;             for (int e = 0; e < 4; ++e) v[e] += P[ww * 2112 + (4 * nq + e) * 33 + tok];
;         const size_t off = (size_t)(t0 + tok) * 1024 + n0 + 4 * nq;
;         if (MODE == 0) {
;             f32x4 b; if (baseb) { const u32x2 bw = *(const u32x2*)(baseb + off); b = (f32x4){bflo(bw.x), bfhi(bw.x), bflo(bw.y), bfhi(bw.y)}; } else b = *(const f32x4*)(base + off);
;             const f32x4 hv = (f32x4){b[0] + alpha * v[0], b[1] + alpha * v[1], b[2] + alpha * v[2], b[3] + alpha * v[3]};
;             if (H) *(f32x4*)(H + off) = hv;
;             if (XN) { u32x2 xw; xw.x = pk2(hv[0], hv[1]); xw.y = pk2(hv[2], hv[3]); *(u32x2*)(XN + off) = xw; }
;             if (SS) { float ss = (hv[0] * hv[0] + hv[1] * hv[1]) + (hv[2] * hv[2] + hv[3] * hv[3]);
;                 ss += __shfl_xor(ss, 1); ss += __shfl_xor(ss, 2); ss += __shfl_xor(ss, 4); ss += __shfl_xor(ss, 8);
;                 if (nq == 0) SS[(size_t)(t0 + tok) * 16 + (n0 >> 6)] = ss; }
	v_mfma_f32_32x32x16_bf16 v[2:17], v[104:107], v[108:111], v[2:17]
	v_mfma_f32_32x32x16_bf16 v[18:33], v[112:115], v[108:111], v[18:33]
	global_load_dwordx4 v[104:107], v[86:87], off offset:640
	global_load_dwordx4 v[108:111], v[88:89], off offset:640
	global_load_dwordx4 v[112:115], v[90:91], off offset:640
	s_waitcnt vmcnt(24)
	v_mfma_f32_32x32x16_bf16 v[2:17], v[116:119], v[120:123], v[2:17]
	v_mfma_f32_32x32x16_bf16 v[18:33], v[124:127], v[120:123], v[18:33]
	global_load_dwordx4 v[116:119], v[86:87], off offset:672
	global_load_dwordx4 v[120:123], v[88:89], off offset:672
	global_load_dwordx4 v[124:127], v[90:91], off offset:672
	s_waitcnt vmcnt(24)
	v_mfma_f32_32x32x16_bf16 v[2:17], v[208:211], v[212:215], v[2:17]
	v_mfma_f32_32x32x16_bf16 v[18:33], v[216:219], v[212:215], v[18:33]
	s_waitcnt vmcnt(21)
	v_mfma_f32_32x32x16_bf16 v[2:17], v[220:223], v[224:227], v[2:17]
	v_mfma_f32_32x32x16_bf16 v[18:33], v[228:231], v[224:227], v[18:33]
	s_waitcnt vmcnt(18)
	v_mfma_f32_32x32x16_bf16 v[2:17], v[232:235], v[236:239], v[2:17]
	v_mfma_f32_32x32x16_bf16 v[18:33], v[166:169], v[236:239], v[18:33]
	s_waitcnt vmcnt(15)
	v_mfma_f32_32x32x16_bf16 v[2:17], v[170:173], v[174:177], v[2:17]
	v_mfma_f32_32x32x16_bf16 v[18:33], v[182:185], v[174:177], v[18:33]
	s_waitcnt vmcnt(12)
	v_mfma_f32_32x32x16_bf16 v[2:17], v[186:189], v[190:193], v[2:17]
	v_mfma_f32_32x32x16_bf16 v[18:33], v[240:243], v[190:193], v[18:33]
	s_waitcnt vmcnt(9)
	v_mfma_f32_32x32x16_bf16 v[2:17], v[72:75], v[76:79], v[2:17]
	v_mfma_f32_32x32x16_bf16 v[18:33], v[80:83], v[76:79], v[18:33]
	s_waitcnt vmcnt(6)
	v_mfma_f32_32x32x16_bf16 v[2:17], v[92:95], v[96:99], v[2:17]
	v_mfma_f32_32x32x16_bf16 v[18:33], v[100:103], v[96:99], v[18:33]
	s_waitcnt vmcnt(3)
	v_mfma_f32_32x32x16_bf16 v[2:17], v[104:107], v[108:111], v[2:17]
	v_mfma_f32_32x32x16_bf16 v[18:33], v[112:115], v[108:111], v[18:33]
	s_waitcnt vmcnt(0)
	v_mfma_f32_32x32x16_bf16 v[2:17], v[116:119], v[120:123], v[2:17]
	v_mfma_f32_32x32x16_bf16 v[18:33], v[124:127], v[120:123], v[18:33]
	s_nop 10
	ds_write2_b32 v43, v2, v3 offset1:33
	v_add_u32_e32 v2, s16, v42
	v_ashrrev_i32_e32 v3, 31, v2
	ds_write2_b32 v45, v18, v19 offset0:32 offset1:65
	ds_write2_b32 v43, v4, v5 offset0:66 offset1:99
	ds_write2_b32 v45, v20, v21 offset0:98 offset1:131
	ds_write2_b32 v46, v6, v7 offset0:8 offset1:41
	ds_write2_b32 v47, v22, v23 offset0:40 offset1:73
	ds_write2_b32 v46, v8, v9 offset0:74 offset1:107
	ds_write2_b32 v47, v24, v25 offset0:106 offset1:139
	ds_write2_b32 v48, v10, v11 offset0:16 offset1:49
	ds_write2_b32 v49, v26, v27 offset0:48 offset1:81
	ds_write2_b32 v48, v12, v13 offset0:82 offset1:115
	ds_write2_b32 v49, v28, v29 offset0:114 offset1:147
	ds_write2_b32 v50, v14, v15 offset0:24 offset1:57
	ds_write2_b32 v51, v30, v31 offset0:56 offset1:89
	ds_write2_b32 v50, v16, v17 offset0:90 offset1:123
	ds_write2_b32 v51, v32, v33 offset0:122 offset1:155
	v_lshlrev_b64 v[8:9], 10, v[2:3]
	v_or_b32_e32 v4, s14, v8
	v_or_b32_e32 v8, v4, v40
	s_waitcnt lgkmcnt(0)
	v_lshl_add_u64 v[4:5], v[8:9], 2, s[6:7]
	s_barrier
	global_load_dwordx4 v[4:7], v[4:5], off
	ds_read2_b32 v[10:11], v44 offset1:33
	ds_read2_b32 v[12:13], v44 offset0:66 offset1:99
	ds_read2_b32 v[14:15], v52 offset0:64 offset1:97
	ds_read2_b32 v[16:17], v52 offset0:130 offset1:163
	ds_read2_b32 v[18:19], v53 offset0:128 offset1:161
	ds_read2_b32 v[20:21], v53 offset0:194 offset1:227
	ds_read2_b32 v[22:23], v54 offset0:192 offset1:225
	ds_read2_b32 v[24:25], v55 offset0:2 offset1:35
	ds_read2_b32 v[26:27], v56 offset1:33
	ds_read2_b32 v[28:29], v56 offset0:66 offset1:99
	ds_read2_b32 v[30:31], v57 offset0:64 offset1:97
	ds_read2_b32 v[32:33], v57 offset0:130 offset1:163
	ds_read2_b32 v[62:63], v58 offset0:128 offset1:161
	ds_read2_b32 v[64:65], v58 offset0:194 offset1:227
	ds_read2_b32 v[66:67], v59 offset0:192 offset1:225
	ds_read2_b32 v[68:69], v60 offset0:2 offset1:35
	s_waitcnt lgkmcnt(14)
	v_pk_add_f32 v[10:11], v[10:11], 0 op_sel_hi:[1,0]
	s_waitcnt lgkmcnt(13)
	v_pk_add_f32 v[10:11], v[10:11], v[14:15]
	s_waitcnt lgkmcnt(11)
	v_pk_add_f32 v[10:11], v[10:11], v[18:19]
	s_waitcnt lgkmcnt(9)
	v_pk_add_f32 v[10:11], v[10:11], v[22:23]
	s_waitcnt lgkmcnt(7)
	v_pk_add_f32 v[10:11], v[10:11], v[26:27]
	s_waitcnt lgkmcnt(5)
	v_pk_add_f32 v[10:11], v[10:11], v[30:31]
	s_waitcnt lgkmcnt(3)
	v_pk_add_f32 v[10:11], v[10:11], v[62:63]
	s_waitcnt lgkmcnt(1)
	v_pk_add_f32 v[10:11], v[10:11], v[66:67]
	s_waitcnt vmcnt(0)
	v_pk_fma_f32 v[10:11], v[10:11], 0.5, v[4:5] op_sel_hi:[1,0,1]
	v_pk_add_f32 v[4:5], v[12:13], 0 op_sel_hi:[1,0]
	s_nop 0
	v_pk_add_f32 v[4:5], v[4:5], v[16:17]
	s_nop 0
	v_pk_add_f32 v[4:5], v[4:5], v[20:21]
	s_nop 0
	v_pk_add_f32 v[4:5], v[4:5], v[24:25]
	s_nop 0
	v_pk_add_f32 v[4:5], v[4:5], v[28:29]
	s_nop 0
	v_pk_add_f32 v[4:5], v[4:5], v[32:33]
	s_nop 0
	v_pk_add_f32 v[4:5], v[4:5], v[64:65]
	s_waitcnt lgkmcnt(0)
	v_pk_add_f32 v[4:5], v[4:5], v[68:69]
	s_nop 0
	v_pk_fma_f32 v[6:7], v[4:5], 0.5, v[6:7] op_sel_hi:[1,0,1]
	v_pk_mul_f32 v[4:5], v[10:11], v[10:11]
	v_pk_mul_f32 v[12:13], v[6:7], v[6:7]
	v_add_f32_e32 v4, v4, v5
	v_add_f32_e32 v12, v12, v13
	v_add_f32_e32 v4, v4, v12
	ds_bpermute_b32 v5, v181, v4
	v_cvt_pk_bf16_f32 v10, v10, v11
	v_cvt_pk_bf16_f32 v11, v6, v7
	v_lshl_add_u64 v[6:7], v[8:9], 1, s[10:11]
	global_store_dwordx2 v[6:7], v[10:11], off
	s_waitcnt lgkmcnt(0)
	v_add_f32_e32 v4, v4, v5
	ds_bpermute_b32 v5, v196, v4
	s_waitcnt lgkmcnt(0)
	v_add_f32_e32 v4, v4, v5
	ds_bpermute_b32 v5, v197, v4
	s_waitcnt lgkmcnt(0)
	v_add_f32_e32 v4, v4, v5
	ds_bpermute_b32 v5, v198, v4
	s_and_saveexec_b64 s[16:17], s[8:9]
	s_cbranch_execz .LBB0_289
	v_lshlrev_b64 v[2:3], 6, v[2:3]
	v_lshl_add_u64 v[2:3], s[12:13], 0, v[2:3]
	s_lshr_b32 s14, s14, 4
	s_waitcnt lgkmcnt(0)
	v_add_f32_e32 v4, v4, v5
	v_lshl_add_u64 v[2:3], v[2:3], 0, s[14:15]
	global_store_dword v[2:3], v4, off
	s_branch .LBB0_289

; #define LAS __attribute__((address_space(3)))
; template <int MODE> __device__ __forceinline__ void small_gemm_res(LAS unsigned char* lds, const bf16* A, const bf16* Bt, int K, const float* base, const bf16* baseb, float* H, bf16* XN, float* SS, float alpha, const bf16* GGs, int bx, int G, int tid) {
;     ...
;         for (int k = 0; k < kw; k += 16) {
;             const bf16x8 x = *(const bf16x8*)(ap + k), w0 = *(const bf16x8*)(b0p + k), w1 = *(const bf16x8*)(b1p + k);
;             acc0 = __builtin_amdgcn_mfma_f32_32x32x16_bf16(w0, x, acc0, 0, 0, 0); acc1 = __builtin_amdgcn_mfma_f32_32x32x16_bf16(w1, x, acc1, 0, 0, 0);
;         }
;         LAS float* Pw = P + w * 2112;
; #pragma unroll
;         for (int r = 0; r < 16; ++r) { Pw[crow(r, hi) * 33 + r32] = acc0[r]; Pw[(32 + crow(r, hi)) * 33 + r32] = acc1[r]; }
;         __syncthreads();
;         const int tok = tid >> 4, nq = tid & 15;
;         float v[4] = {0.f, 0.f, 0.f, 0.f};
; #pragma unroll
;         for (int ww = 0; ww < 8; ++ww)
; #pragma unroll
;             for (int e = 0; e < 4; ++e) v[e] += P[ww * 2112 + (4 * nq + e) * 33 + tok];
;         const size_t off = (size_t)(t0 + tok) * 1024 + n0 + 4 * nq;
;         if (MODE == 0) {
;             f32x4 b; if (baseb) { const u32x2 bw = *(const u32x2*)(baseb + off); b = (f32x4){bflo(bw.x), bfhi(bw.x), bflo(bw.y), bfhi(bw.y)}; } else b = *(const f32x4*)(base + off);
;             const f32x4 hv = (f32x4){b[0] + alpha * v[0], b[1] + alpha * v[1], b[2] + alpha * v[2], b[3] + alpha * v[3]};
;             if (H) *(f32x4*)(H + off) = hv;
;             if (XN) { u32x2 xw; xw.x = pk2(hv[0], hv[1]); xw.y = pk2(hv[2], hv[3]); *(u32x2*)(XN + off) = xw; }
;             if (SS) { float ss = (hv[0] * hv[0] + hv[1] * hv[1]) + (hv[2] * hv[2] + hv[3] * hv[3]);
;                 ss += __shfl_xor(ss, 1); ss += __shfl_xor(ss, 2); ss += __shfl_xor(ss, 4); ss += __shfl_xor(ss, 8);
;                 if (nq == 0) SS[(size_t)(t0 + tok) * 16 + (n0 >> 6)] = ss; }
;         } else {
;             const u32x2 gw = *(const u32x2*)(GGs + (size_t)(t0 + tok) * 2048 + n0 + 4 * nq);
;             f32x4 o = (f32x4){pg8::fast_sigmoid(bflo(gw.x)) * v[0], pg8::fast_sigmoid(bfhi(gw.x)) * v[1], pg8::fast_sigmoid(bflo(gw.y)) * v[2], pg8::fast_sigmoid(bfhi(gw.y)) * v[3]};
;             if (MODE == 1) { u32x2 xw; xw.x = pk2(o[0], o[1]); xw.y = pk2(o[2], o[3]); *(u32x2*)(XN + off) = xw; }
.LBB0_775:
	v_lshl_add_u64 v[58:59], v[42:43], 0, v[2:3]
	s_mov_b32 s20, 0x2100000
	v_add_co_u32_e32 v64, vcc, s20, v58
	s_mov_b32 s20, 0x2110000
	s_nop 0
	v_addc_co_u32_e32 v65, vcc, 0, v59, vcc
	v_add_co_u32_e32 v66, vcc, s20, v58
	v_lshl_add_u64 v[62:63], v[42:43], 0, v[40:41]
	s_nop 0
	v_addc_co_u32_e32 v67, vcc, 0, v59, vcc
	s_add_i32 s7, s7, 64
	v_lshl_add_u64 v[42:43], v[42:43], 0, s[76:77]
	s_cmpk_gt_u32 s7, 0x6f
	global_load_dwordx4 v[68:71], v[62:63], off offset:-64
	global_load_dwordx4 v[72:75], v[64:65], off
	global_load_dwordx4 v[76:79], v[66:67], off
	global_load_dwordx4 v[80:83], v[62:63], off offset:-32
	global_load_dwordx4 v[92:95], v[64:65], off offset:32
	global_load_dwordx4 v[96:99], v[66:67], off offset:32
	global_load_dwordx4 v[100:103], v[62:63], off
	global_load_dwordx4 v[104:107], v[64:65], off offset:64
	global_load_dwordx4 v[108:111], v[66:67], off offset:64
	global_load_dwordx4 v[112:115], v[62:63], off offset:32
	global_load_dwordx4 v[116:119], v[64:65], off offset:96
	global_load_dwordx4 v[120:123], v[66:67], off offset:96
	s_waitcnt vmcnt(9)
	v_mfma_f32_32x32x16_bf16 v[4:19], v[72:75], v[68:71], v[4:19]
	v_mfma_f32_32x32x16_bf16 v[20:35], v[76:79], v[68:71], v[20:35]
	s_waitcnt vmcnt(6)
	v_mfma_f32_32x32x16_bf16 v[4:19], v[92:95], v[80:83], v[4:19]
	v_mfma_f32_32x32x16_bf16 v[20:35], v[96:99], v[80:83], v[20:35]
	s_waitcnt vmcnt(3)
	v_mfma_f32_32x32x16_bf16 v[4:19], v[104:107], v[100:103], v[4:19]
	v_mfma_f32_32x32x16_bf16 v[20:35], v[108:111], v[100:103], v[20:35]
	s_waitcnt vmcnt(0)
	v_mfma_f32_32x32x16_bf16 v[4:19], v[116:119], v[112:115], v[4:19]
	v_mfma_f32_32x32x16_bf16 v[20:35], v[120:123], v[112:115], v[20:35]
	s_cbranch_scc0 .LBB0_775
	v_add_u32_e32 v2, 0x1000, v46
	s_nop 8
	ds_write2_b32 v46, v4, v5 offset1:33
	s_nop 0
	ds_write2_b32 v2, v20, v21 offset0:32 offset1:65
	ds_write2_b32 v46, v6, v7 offset0:66 offset1:99
	ds_write2_b32 v2, v22, v23 offset0:98 offset1:131
	v_add_u32_e32 v2, 0x400, v46
	v_add_u32_e32 v4, 0x1400, v46
	s_lshl_b32 s7, s6, 1
	ds_write2_b32 v2, v8, v9 offset0:8 offset1:41
	ds_write2_b32 v4, v24, v25 offset0:40 offset1:73
	ds_write2_b32 v2, v10, v11 offset0:74 offset1:107
	ds_write2_b32 v4, v26, v27 offset0:106 offset1:139
	v_add_u32_e32 v2, 0x800, v46
	v_add_u32_e32 v4, 0x1800, v46
	s_andn2_b32 s7, s7, 31
	ds_write2_b32 v2, v12, v13 offset0:16 offset1:49
	ds_write2_b32 v4, v28, v29 offset0:48 offset1:81
	ds_write2_b32 v2, v14, v15 offset0:82 offset1:115
	ds_write2_b32 v4, v30, v31 offset0:114 offset1:147
	v_add_u32_e32 v2, 0xc00, v46
	v_add_u32_e32 v4, 0x1c00, v46
	ds_write2_b32 v2, v16, v17 offset0:24 offset1:57
	ds_write2_b32 v4, v32, v33 offset0:56 offset1:89
	ds_write2_b32 v2, v18, v19 offset0:90 offset1:123
	ds_write2_b32 v4, v34, v35 offset0:122 offset1:155
	v_add_u32_e32 v4, s7, v45
	v_ashrrev_i32_e32 v5, 31, v4
	v_lshlrev_b64 v[6:7], 12, v[4:5]
	s_lshl_b32 s7, s6, 7
	v_lshl_add_u64 v[6:7], s[10:11], 0, v[6:7]
	s_and_b32 s78, s7, 0x780
	v_lshl_add_u64 v[6:7], v[6:7], 0, s[78:79]
	v_mov_b32_e32 v39, v3
	v_lshl_add_u64 v[6:7], v[6:7], 0, v[38:39]
	s_waitcnt lgkmcnt(0)
	s_barrier
	global_load_dwordx2 v[6:7], v[6:7], off
	v_add_u32_e32 v18, 0x4000, v48
	v_add_u32_e32 v20, 0x6000, v48
	v_add_u32_e32 v22, 0x6400, v48
	v_add_u32_e32 v26, 0x8400, v48
	v_add_u32_e32 v30, 0xa400, v48
	v_add_u32_e32 v34, 0xc400, v48
	v_add_u32_e32 v40, 0xe400, v48
	v_add_u32_e32 v42, 0xe800, v48
	v_add_u32_e32 v2, 0x2000, v48
	ds_read2_b32 v[8:9], v48 offset1:33
	ds_read2_b32 v[10:11], v48 offset0:66 offset1:99
	ds_read2_b32 v[12:13], v2 offset0:64 offset1:97
	ds_read2_b32 v[14:15], v2 offset0:130 offset1:163
	ds_read2_b32 v[16:17], v18 offset0:128 offset1:161
	ds_read2_b32 v[18:19], v18 offset0:194 offset1:227
	ds_read2_b32 v[20:21], v20 offset0:192 offset1:225
	ds_read2_b32 v[22:23], v22 offset0:2 offset1:35
	ds_read2_b32 v[24:25], v26 offset1:33
	ds_read2_b32 v[26:27], v26 offset0:66 offset1:99
	ds_read2_b32 v[28:29], v30 offset0:64 offset1:97
	ds_read2_b32 v[30:31], v30 offset0:130 offset1:163
	ds_read2_b32 v[32:33], v34 offset0:128 offset1:161
	ds_read2_b32 v[34:35], v34 offset0:194 offset1:227
	ds_read2_b32 v[40:41], v40 offset0:192 offset1:225
	ds_read2_b32 v[42:43], v42 offset0:2 offset1:35
	s_waitcnt lgkmcnt(14)
	v_pk_add_f32 v[8:9], v[8:9], 0 op_sel_hi:[1,0]
	v_pk_add_f32 v[10:11], v[10:11], 0 op_sel_hi:[1,0]
	s_waitcnt lgkmcnt(13)
	v_pk_add_f32 v[8:9], v[8:9], v[12:13]
	s_waitcnt lgkmcnt(12)
	v_pk_add_f32 v[10:11], v[10:11], v[14:15]
	s_waitcnt lgkmcnt(11)
	v_pk_add_f32 v[8:9], v[8:9], v[16:17]
	s_waitcnt lgkmcnt(10)
	v_pk_add_f32 v[10:11], v[10:11], v[18:19]
	s_waitcnt lgkmcnt(9)
	v_pk_add_f32 v[8:9], v[8:9], v[20:21]
	s_waitcnt lgkmcnt(8)
	v_pk_add_f32 v[10:11], v[10:11], v[22:23]
	s_waitcnt lgkmcnt(7)
	v_pk_add_f32 v[8:9], v[8:9], v[24:25]
	s_waitcnt lgkmcnt(6)
	v_pk_add_f32 v[10:11], v[10:11], v[26:27]
	s_waitcnt lgkmcnt(5)
	v_pk_add_f32 v[8:9], v[8:9], v[28:29]
	s_waitcnt lgkmcnt(4)
	v_pk_add_f32 v[10:11], v[10:11], v[30:31]
	s_waitcnt lgkmcnt(3)
	v_pk_add_f32 v[8:9], v[8:9], v[32:33]
	s_waitcnt lgkmcnt(2)
	v_pk_add_f32 v[10:11], v[10:11], v[34:35]
	v_lshlrev_b64 v[4:5], 11, v[4:5]
	v_readlane_b32 s0, v251, 44
	s_waitcnt lgkmcnt(1)
	v_pk_add_f32 v[8:9], v[8:9], v[40:41]
	s_waitcnt lgkmcnt(0)
	v_pk_add_f32 v[10:11], v[10:11], v[42:43]
	v_lshl_add_u64 v[4:5], s[4:5], 0, v[4:5]
	s_add_i32 s3, s3, s0
	v_readlane_b32 s0, v251, 48
	v_lshl_add_u64 v[4:5], v[4:5], 0, s[78:79]
	s_add_i32 s6, s6, s70
	s_add_i32 s2, s2, s0
	v_lshl_add_u64 v[4:5], v[4:5], 0, v[38:39]
	s_cmpk_gt_i32 s6, 0xff
	s_waitcnt vmcnt(0)
	v_lshlrev_b32_e32 v2, 16, v6
	v_and_b32_e32 v6, 0xffff0000, v6
	v_lshlrev_b32_e32 v12, 16, v7
	v_and_b32_e32 v7, 0xffff0000, v7
	v_mul_f32_e32 v2, 0xbfb8aa3b, v2
	v_mul_f32_e32 v6, 0xbfb8aa3b, v6
	v_mul_f32_e32 v12, 0xbfb8aa3b, v12
	v_mul_f32_e32 v7, 0xbfb8aa3b, v7
	v_exp_f32_e32 v2, v2
	v_exp_f32_e32 v6, v6
	v_exp_f32_e32 v12, v12
	v_exp_f32_e32 v7, v7
	v_add_f32_e32 v2, 1.0, v2
	v_add_f32_e32 v13, 1.0, v6
	v_add_f32_e32 v12, 1.0, v12
	v_add_f32_e32 v14, 1.0, v7
	v_rcp_f32_e32 v6, v2
	v_rcp_f32_e32 v7, v13
	v_rcp_f32_e32 v12, v12
	v_rcp_f32_e32 v13, v14
	v_pk_mul_f32 v[6:7], v[8:9], v[6:7]
	s_nop 0
	v_cvt_pk_bf16_f32 v6, v6, v7
	v_pk_mul_f32 v[8:9], v[10:11], v[12:13]
	s_nop 0
	v_cvt_pk_bf16_f32 v7, v8, v9
	global_store_dwordx2 v[4:5], v[6:7], off
	s_barrier
	s_cbranch_scc0 .LBB0_774

; #define LAS __attribute__((address_space(3)))
; template <int MODE> __device__ __forceinline__ void small_gemm_res(LAS unsigned char* lds, const bf16* A, const bf16* Bt, int K, const float* base, const bf16* baseb, float* H, bf16* XN, float* SS, float alpha, const bf16* GGs, int bx, int G, int tid) {
;     ...
;         for (int k = 0; k < kw; k += 16) {
;             const bf16x8 x = *(const bf16x8*)(ap + k), w0 = *(const bf16x8*)(b0p + k), w1 = *(const bf16x8*)(b1p + k);
;             acc0 = __builtin_amdgcn_mfma_f32_32x32x16_bf16(w0, x, acc0, 0, 0, 0); acc1 = __builtin_amdgcn_mfma_f32_32x32x16_bf16(w1, x, acc1, 0, 0, 0);
;         }
;         LAS float* Pw = P + w * 2112;
; #pragma unroll
;         for (int r = 0; r < 16; ++r) { Pw[crow(r, hi) * 33 + r32] = acc0[r]; Pw[(32 + crow(r, hi)) * 33 + r32] = acc1[r]; }
;         __syncthreads();
;         const int tok = tid >> 4, nq = tid & 15;
;         float v[4] = {0.f, 0.f, 0.f, 0.f};
; #pragma unroll
;         for (int ww = 0; ww < 8; ++ww)
; #pragma unroll
;             for (int e = 0; e < 4; ++e) v[e] += P[ww * 2112 + (4 * nq + e) * 33 + tok];
;         const size_t off = (size_t)(t0 + tok) * 1024 + n0 + 4 * nq;
;         if (MODE == 0) {
;             f32x4 b; if (baseb) { const u32x2 bw = *(const u32x2*)(baseb + off); b = (f32x4){bflo(bw.x), bfhi(bw.x), bflo(bw.y), bfhi(bw.y)}; } else b = *(const f32x4*)(base + off);
;             const f32x4 hv = (f32x4){b[0] + alpha * v[0], b[1] + alpha * v[1], b[2] + alpha * v[2], b[3] + alpha * v[3]};
;             if (H) *(f32x4*)(H + off) = hv;
;             if (XN) { u32x2 xw; xw.x = pk2(hv[0], hv[1]); xw.y = pk2(hv[2], hv[3]); *(u32x2*)(XN + off) = xw; }
;             if (SS) { float ss = (hv[0] * hv[0] + hv[1] * hv[1]) + (hv[2] * hv[2] + hv[3] * hv[3]);
;                 ss += __shfl_xor(ss, 1); ss += __shfl_xor(ss, 2); ss += __shfl_xor(ss, 4); ss += __shfl_xor(ss, 8);
;                 if (nq == 0) SS[(size_t)(t0 + tok) * 16 + (n0 >> 6)] = ss; }
;         } else {
;             const u32x2 gw = *(const u32x2*)(GGs + (size_t)(t0 + tok) * 2048 + n0 + 4 * nq);
;             f32x4 o = (f32x4){pg8::fast_sigmoid(bflo(gw.x)) * v[0], pg8::fast_sigmoid(bfhi(gw.x)) * v[1], pg8::fast_sigmoid(bflo(gw.y)) * v[2], pg8::fast_sigmoid(bfhi(gw.y)) * v[3]};
;             if (MODE == 1) { u32x2 xw; xw.x = pk2(o[0], o[1]); xw.y = pk2(o[2], o[3]); *(u32x2*)(XN + off) = xw; }
.LBB0_801:
	v_lshl_add_u64 v[56:57], v[42:43], 0, v[2:3]
	s_mov_b32 s14, 0x2300000
	v_add_co_u32_e32 v62, vcc, s14, v56
	s_mov_b32 s14, 0x2310000
	s_nop 0
	v_addc_co_u32_e32 v63, vcc, 0, v57, vcc
	v_add_co_u32_e32 v64, vcc, s14, v56
	v_lshl_add_u64 v[60:61], v[42:43], 0, v[40:41]
	s_nop 0
	v_addc_co_u32_e32 v65, vcc, 0, v57, vcc
	s_add_i32 s7, s7, 64
	v_lshl_add_u64 v[42:43], v[42:43], 0, s[76:77]
	s_cmpk_gt_u32 s7, 0x6f
	global_load_dwordx4 v[68:71], v[60:61], off offset:-64
	global_load_dwordx4 v[72:75], v[62:63], off
	global_load_dwordx4 v[76:79], v[64:65], off
	global_load_dwordx4 v[80:83], v[60:61], off offset:-32
	global_load_dwordx4 v[92:95], v[62:63], off offset:32
	global_load_dwordx4 v[96:99], v[64:65], off offset:32
	global_load_dwordx4 v[100:103], v[60:61], off
	global_load_dwordx4 v[104:107], v[62:63], off offset:64
	global_load_dwordx4 v[108:111], v[64:65], off offset:64
	global_load_dwordx4 v[112:115], v[60:61], off offset:32
	global_load_dwordx4 v[116:119], v[62:63], off offset:96
	global_load_dwordx4 v[120:123], v[64:65], off offset:96
	s_waitcnt vmcnt(9)
	v_mfma_f32_32x32x16_bf16 v[4:19], v[72:75], v[68:71], v[4:19]
	v_mfma_f32_32x32x16_bf16 v[20:35], v[76:79], v[68:71], v[20:35]
	s_waitcnt vmcnt(6)
	v_mfma_f32_32x32x16_bf16 v[4:19], v[92:95], v[80:83], v[4:19]
	v_mfma_f32_32x32x16_bf16 v[20:35], v[96:99], v[80:83], v[20:35]
	s_waitcnt vmcnt(3)
	v_mfma_f32_32x32x16_bf16 v[4:19], v[104:107], v[100:103], v[4:19]
	v_mfma_f32_32x32x16_bf16 v[20:35], v[108:111], v[100:103], v[20:35]
	s_waitcnt vmcnt(0)
	v_mfma_f32_32x32x16_bf16 v[4:19], v[116:119], v[112:115], v[4:19]
	v_mfma_f32_32x32x16_bf16 v[20:35], v[120:123], v[112:115], v[20:35]
	s_cbranch_scc0 .LBB0_801
	v_add_u32_e32 v2, 0x1000, v45
	s_nop 8
	ds_write2_b32 v45, v4, v5 offset1:33
	s_nop 0
	ds_write2_b32 v2, v20, v21 offset0:32 offset1:65
	ds_write2_b32 v45, v6, v7 offset0:66 offset1:99
	ds_write2_b32 v2, v22, v23 offset0:98 offset1:131
	v_add_u32_e32 v2, 0x400, v45
	v_add_u32_e32 v4, 0x1400, v45
	s_lshl_b32 s7, s6, 1
	ds_write2_b32 v2, v8, v9 offset0:8 offset1:41
	ds_write2_b32 v4, v24, v25 offset0:40 offset1:73
	ds_write2_b32 v2, v10, v11 offset0:74 offset1:107
	ds_write2_b32 v4, v26, v27 offset0:106 offset1:139
	v_add_u32_e32 v2, 0x800, v45
	v_add_u32_e32 v4, 0x1800, v45
	s_andn2_b32 s7, s7, 31
	ds_write2_b32 v2, v12, v13 offset0:16 offset1:49
	ds_write2_b32 v4, v28, v29 offset0:48 offset1:81
	ds_write2_b32 v2, v14, v15 offset0:82 offset1:115
	ds_write2_b32 v4, v30, v31 offset0:114 offset1:147
	v_add_u32_e32 v2, 0xc00, v45
	v_add_u32_e32 v4, 0x1c00, v45
	ds_write2_b32 v2, v16, v17 offset0:24 offset1:57
	ds_write2_b32 v4, v32, v33 offset0:56 offset1:89
	ds_write2_b32 v2, v18, v19 offset0:90 offset1:123
	ds_write2_b32 v4, v34, v35 offset0:122 offset1:155
	v_add_u32_e32 v4, s7, v44
	s_lshl_b32 s14, s6, 6
	v_ashrrev_i32_e32 v5, 31, v4
	s_and_b32 s14, s14, 0x3c0
	v_lshlrev_b64 v[6:7], 12, v[4:5]
	v_lshl_add_u64 v[6:7], s[18:19], 0, v[6:7]
	s_lshl_b32 s78, s14, 1
	v_lshl_add_u64 v[6:7], v[6:7], 0, s[78:79]
	v_lshlrev_b32_e32 v2, 1, v36
	v_lshl_add_u64 v[6:7], v[6:7], 0, v[2:3]
	s_waitcnt lgkmcnt(0)
	s_barrier
	global_load_dwordx2 v[6:7], v[6:7], off
	v_lshlrev_b64 v[4:5], 10, v[4:5]
	v_or_b32_e32 v2, s14, v4
	v_or_b32_e32 v4, v2, v36
	v_lshlrev_b64 v[4:5], 1, v[4:5]
	v_lshl_add_u64 v[8:9], s[4:5], 0, v[4:5]
	global_load_dwordx2 v[8:9], v[8:9], off
	v_add_u32_e32 v20, 0x4000, v47
	v_add_u32_e32 v22, 0x6000, v47
	v_add_u32_e32 v24, 0x6400, v47
	v_add_u32_e32 v28, 0x8400, v47
	v_add_u32_e32 v32, 0xa400, v47
	v_add_u32_e32 v40, 0xc400, v47
	v_add_u32_e32 v42, 0xe400, v47
	v_add_u32_e32 v48, 0xe800, v47
	v_add_u32_e32 v2, 0x2000, v47
	ds_read2_b32 v[10:11], v47 offset1:33
	ds_read2_b32 v[12:13], v47 offset0:66 offset1:99
	ds_read2_b32 v[14:15], v2 offset0:64 offset1:97
	ds_read2_b32 v[16:17], v2 offset0:130 offset1:163
	ds_read2_b32 v[18:19], v20 offset0:128 offset1:161
	ds_read2_b32 v[20:21], v20 offset0:194 offset1:227
	ds_read2_b32 v[22:23], v22 offset0:192 offset1:225
	ds_read2_b32 v[24:25], v24 offset0:2 offset1:35
	ds_read2_b32 v[26:27], v28 offset1:33
	ds_read2_b32 v[28:29], v28 offset0:66 offset1:99
	ds_read2_b32 v[30:31], v32 offset0:64 offset1:97
	ds_read2_b32 v[32:33], v32 offset0:130 offset1:163
	ds_read2_b32 v[34:35], v40 offset0:128 offset1:161
	ds_read2_b32 v[40:41], v40 offset0:194 offset1:227
	ds_read2_b32 v[42:43], v42 offset0:192 offset1:225
	ds_read2_b32 v[48:49], v48 offset0:2 offset1:35
	s_waitcnt lgkmcnt(14)
	v_pk_add_f32 v[10:11], v[10:11], 0 op_sel_hi:[1,0]
	v_pk_add_f32 v[12:13], v[12:13], 0 op_sel_hi:[1,0]
	s_waitcnt lgkmcnt(13)
	v_pk_add_f32 v[10:11], v[10:11], v[14:15]
	s_waitcnt lgkmcnt(12)
	v_pk_add_f32 v[12:13], v[12:13], v[16:17]
	s_waitcnt lgkmcnt(11)
	v_pk_add_f32 v[10:11], v[10:11], v[18:19]
	s_waitcnt lgkmcnt(10)
	v_pk_add_f32 v[12:13], v[12:13], v[20:21]
	s_waitcnt lgkmcnt(9)
	v_pk_add_f32 v[10:11], v[10:11], v[22:23]
	s_waitcnt lgkmcnt(8)
	v_pk_add_f32 v[12:13], v[12:13], v[24:25]
	s_waitcnt lgkmcnt(7)
	v_pk_add_f32 v[10:11], v[10:11], v[26:27]
	s_waitcnt lgkmcnt(6)
	v_pk_add_f32 v[12:13], v[12:13], v[28:29]
	s_waitcnt lgkmcnt(5)
	v_pk_add_f32 v[10:11], v[10:11], v[30:31]
	s_waitcnt lgkmcnt(4)
	v_pk_add_f32 v[12:13], v[12:13], v[32:33]
	s_waitcnt lgkmcnt(3)
	v_pk_add_f32 v[10:11], v[10:11], v[34:35]
	s_waitcnt lgkmcnt(2)
	v_pk_add_f32 v[12:13], v[12:13], v[40:41]
	v_readlane_b32 s0, v251, 44
	s_waitcnt lgkmcnt(1)
	v_pk_add_f32 v[10:11], v[10:11], v[42:43]
	s_waitcnt lgkmcnt(0)
	v_pk_add_f32 v[12:13], v[12:13], v[48:49]
	s_add_i32 s3, s3, s0
	v_readlane_b32 s0, v251, 48
	s_add_i32 s6, s6, s70
	s_add_i32 s2, s2, s0
	v_lshl_add_u64 v[4:5], s[16:17], 0, v[4:5]
	s_cmpk_gt_i32 s6, 0xff
	s_waitcnt vmcnt(1)
	v_lshlrev_b32_e32 v2, 16, v6
	v_and_b32_e32 v6, 0xffff0000, v6
	v_lshlrev_b32_e32 v14, 16, v7
	v_and_b32_e32 v7, 0xffff0000, v7
	v_mul_f32_e32 v2, 0xbfb8aa3b, v2
	v_mul_f32_e32 v6, 0xbfb8aa3b, v6
	v_mul_f32_e32 v14, 0xbfb8aa3b, v14
	v_mul_f32_e32 v7, 0xbfb8aa3b, v7
	v_exp_f32_e32 v2, v2
	v_exp_f32_e32 v6, v6
	v_exp_f32_e32 v14, v14
	v_exp_f32_e32 v7, v7
	v_add_f32_e32 v2, 1.0, v2
	v_add_f32_e32 v15, 1.0, v6
	v_add_f32_e32 v14, 1.0, v14
	v_add_f32_e32 v16, 1.0, v7
	v_rcp_f32_e32 v6, v2
	v_rcp_f32_e32 v7, v15
	v_rcp_f32_e32 v14, v14
	v_rcp_f32_e32 v15, v16
	s_waitcnt vmcnt(0)
	v_lshlrev_b32_e32 v16, 16, v8
	v_and_b32_e32 v17, 0xffff0000, v8
	v_lshlrev_b32_e32 v8, 16, v9
	v_and_b32_e32 v9, 0xffff0000, v9
	v_pk_fma_f32 v[8:9], v[12:13], v[14:15], v[8:9]
	v_pk_fma_f32 v[6:7], v[10:11], v[6:7], v[16:17]
	s_nop 0
	v_cvt_pk_bf16_f32 v6, v6, v7
	v_cvt_pk_bf16_f32 v7, v8, v9
	global_store_dwordx2 v[4:5], v[6:7], off
	s_barrier
	s_cbranch_scc0 .LBB0_800

; #define LAS __attribute__((address_space(3)))
; __device__ __forceinline__ unsigned pk2(float lo, float hi) { return pg8::cvt_pk_bf16(lo, hi); }
; __device__ __forceinline__ float bflo(unsigned w) { return __uint_as_float(w << 16); }
; __device__ __forceinline__ float bfhi(unsigned w) { return __uint_as_float(w & 0xffff0000u); }
; __device__ __forceinline__ int crow(int r, int hi) { return (r & 3) + 8 * (r >> 2) + 4 * hi; }
; template <int MODE> __device__ __forceinline__ void small_gemm_res(LAS unsigned char* lds, const bf16* A, const bf16* Bt, int K, const float* base, const bf16* baseb, float* H, bf16* XN, float* SS, float alpha, const bf16* GGs, int bx, int G, int tid) {
;     ...
;         for (int k = 0; k < kw; k += 16) {
;             const bf16x8 x = *(const bf16x8*)(ap + k), w0 = *(const bf16x8*)(b0p + k), w1 = *(const bf16x8*)(b1p + k);
;             acc0 = __builtin_amdgcn_mfma_f32_32x32x16_bf16(w0, x, acc0, 0, 0, 0); acc1 = __builtin_amdgcn_mfma_f32_32x32x16_bf16(w1, x, acc1, 0, 0, 0);
;         }
;         LAS float* Pw = P + w * 2112;
; #pragma unroll
;         for (int r = 0; r < 16; ++r) { Pw[crow(r, hi) * 33 + r32] = acc0[r]; Pw[(32 + crow(r, hi)) * 33 + r32] = acc1[r]; }
;         __syncthreads();
;         const int tok = tid >> 4, nq = tid & 15;
;         float v[4] = {0.f, 0.f, 0.f, 0.f};
; #pragma unroll
;         for (int ww = 0; ww < 8; ++ww)
; #pragma unroll
;             for (int e = 0; e < 4; ++e) v[e] += P[ww * 2112 + (4 * nq + e) * 33 + tok];
;         const size_t off = (size_t)(t0 + tok) * 1024 + n0 + 4 * nq;
;         if (MODE == 0) {
;             f32x4 b; if (baseb) { const u32x2 bw = *(const u32x2*)(baseb + off); b = (f32x4){bflo(bw.x), bfhi(bw.x), bflo(bw.y), bfhi(bw.y)}; } else b = *(const f32x4*)(base + off);
;             const f32x4 hv = (f32x4){b[0] + alpha * v[0], b[1] + alpha * v[1], b[2] + alpha * v[2], b[3] + alpha * v[3]};
;             if (H) *(f32x4*)(H + off) = hv;
;             if (XN) { u32x2 xw; xw.x = pk2(hv[0], hv[1]); xw.y = pk2(hv[2], hv[3]); *(u32x2*)(XN + off) = xw; }
;             if (SS) { float ss = (hv[0] * hv[0] + hv[1] * hv[1]) + (hv[2] * hv[2] + hv[3] * hv[3]);
;                 ss += __shfl_xor(ss, 1); ss += __shfl_xor(ss, 2); ss += __shfl_xor(ss, 4); ss += __shfl_xor(ss, 8);
;                 if (nq == 0) SS[(size_t)(t0 + tok) * 16 + (n0 >> 6)] = ss; }
.LBB0_1009:
	v_lshl_add_u64 v[60:61], v[42:43], 0, s[16:17]
	s_mov_b32 s5, 0x2500000
	v_add_co_u32_e64 v66, s[10:11], s5, v60
	s_mov_b32 s5, 0x2510000
	s_nop 0
	v_addc_co_u32_e64 v67, s[10:11], 0, v61, s[10:11]
	v_add_co_u32_e64 v68, s[10:11], s5, v60
	s_nop 1
	v_addc_co_u32_e64 v69, s[10:11], 0, v61, s[10:11]
	v_lshl_add_u64 v[64:65], v[44:45], 0, s[16:17]
	s_add_i32 s4, s4, 64
	v_lshl_add_u64 v[42:43], v[42:43], 0, s[76:77]
	v_lshl_add_u64 v[44:45], v[44:45], 0, s[76:77]
	s_cmpk_gt_u32 s4, 0x6f
	global_load_dwordx4 v[72:75], v[66:67], off
	global_load_dwordx4 v[76:79], v[68:69], off
	global_load_dwordx4 v[80:83], v[64:65], off offset:-64
	global_load_dwordx4 v[92:95], v[64:65], off offset:-32
	global_load_dwordx4 v[96:99], v[66:67], off offset:32
	global_load_dwordx4 v[100:103], v[68:69], off offset:32
	global_load_dwordx4 v[104:107], v[64:65], off
	global_load_dwordx4 v[108:111], v[66:67], off offset:64
	global_load_dwordx4 v[112:115], v[68:69], off offset:64
	global_load_dwordx4 v[116:119], v[64:65], off offset:32
	global_load_dwordx4 v[120:123], v[66:67], off offset:96
	global_load_dwordx4 v[124:127], v[68:69], off offset:96
	s_waitcnt vmcnt(9)
	v_mfma_f32_32x32x16_bf16 v[4:19], v[72:75], v[80:83], v[4:19]
	v_mfma_f32_32x32x16_bf16 v[20:35], v[76:79], v[80:83], v[20:35]
	s_waitcnt vmcnt(6)
	v_mfma_f32_32x32x16_bf16 v[4:19], v[96:99], v[92:95], v[4:19]
	v_mfma_f32_32x32x16_bf16 v[20:35], v[100:103], v[92:95], v[20:35]
	s_waitcnt vmcnt(3)
	v_mfma_f32_32x32x16_bf16 v[4:19], v[108:111], v[104:107], v[4:19]
	v_mfma_f32_32x32x16_bf16 v[20:35], v[112:115], v[104:107], v[20:35]
	s_waitcnt vmcnt(0)
	v_mfma_f32_32x32x16_bf16 v[4:19], v[120:123], v[116:119], v[4:19]
	v_mfma_f32_32x32x16_bf16 v[20:35], v[124:127], v[116:119], v[20:35]
	s_cbranch_scc0 .LBB0_1009
	v_add_u32_e32 v2, 0x1000, v48
	s_nop 8
	ds_write2_b32 v48, v4, v5 offset1:33
	s_nop 0
	ds_write2_b32 v2, v20, v21 offset0:32 offset1:65
	ds_write2_b32 v48, v6, v7 offset0:66 offset1:99
	ds_write2_b32 v2, v22, v23 offset0:98 offset1:131
	v_add_u32_e32 v2, 0x400, v48
	v_add_u32_e32 v4, 0x1400, v48
	s_lshl_b32 s4, s6, 1
	ds_write2_b32 v2, v8, v9 offset0:8 offset1:41
	ds_write2_b32 v4, v24, v25 offset0:40 offset1:73
	ds_write2_b32 v2, v10, v11 offset0:74 offset1:107
	ds_write2_b32 v4, v26, v27 offset0:106 offset1:139
	v_add_u32_e32 v2, 0x800, v48
	v_add_u32_e32 v4, 0x1800, v48
	s_andn2_b32 s4, s4, 31
	ds_write2_b32 v2, v12, v13 offset0:16 offset1:49
	ds_write2_b32 v4, v28, v29 offset0:48 offset1:81
	ds_write2_b32 v2, v14, v15 offset0:82 offset1:115
	ds_write2_b32 v4, v30, v31 offset0:114 offset1:147
	v_add_u32_e32 v2, 0xc00, v48
	v_add_u32_e32 v4, 0x1c00, v48
	ds_write2_b32 v2, v16, v17 offset0:24 offset1:57
	ds_write2_b32 v4, v32, v33 offset0:56 offset1:89
	ds_write2_b32 v2, v18, v19 offset0:90 offset1:123
	ds_write2_b32 v4, v34, v35 offset0:122 offset1:155
	v_add_u32_e32 v4, s4, v47
	s_lshl_b32 s5, s6, 6
	v_ashrrev_i32_e32 v5, 31, v4
	s_and_b32 s7, s5, 0x3c0
	v_lshlrev_b64 v[6:7], 11, v[4:5]
	v_lshl_add_u64 v[6:7], s[12:13], 0, v[6:7]
	s_lshl_b32 s78, s7, 1
	v_lshl_add_u64 v[6:7], v[6:7], 0, s[78:79]
	v_mov_b32_e32 v41, v3
	v_lshl_add_u64 v[8:9], v[6:7], 0, v[40:41]
	s_waitcnt lgkmcnt(0)
	s_barrier
	global_load_dwordx2 v[6:7], v[8:9], off
	v_add_u32_e32 v20, 0x4000, v50
	v_add_u32_e32 v22, 0x6000, v50
	v_add_u32_e32 v24, 0x6400, v50
	v_add_u32_e32 v28, 0x8400, v50
	v_add_u32_e32 v32, 0xa400, v50
	v_add_u32_e32 v44, 0xe400, v50
	v_add_u32_e32 v2, 0x2000, v50
	v_add_u32_e32 v41, 0xc400, v50
	v_add_u32_e32 v51, 0xe800, v50
	ds_read2_b32 v[10:11], v50 offset1:33
	ds_read2_b32 v[12:13], v50 offset0:66 offset1:99
	ds_read2_b32 v[14:15], v2 offset0:64 offset1:97
	ds_read2_b32 v[16:17], v2 offset0:130 offset1:163
	ds_read2_b32 v[18:19], v20 offset0:128 offset1:161
	ds_read2_b32 v[20:21], v20 offset0:194 offset1:227
	ds_read2_b32 v[22:23], v22 offset0:192 offset1:225
	ds_read2_b32 v[24:25], v24 offset0:2 offset1:35
	ds_read2_b32 v[26:27], v28 offset1:33
	ds_read2_b32 v[28:29], v28 offset0:66 offset1:99
	ds_read2_b32 v[30:31], v32 offset0:64 offset1:97
	ds_read2_b32 v[32:33], v32 offset0:130 offset1:163
	ds_read2_b32 v[34:35], v41 offset0:128 offset1:161
	ds_read2_b32 v[42:43], v41 offset0:194 offset1:227
	ds_read2_b32 v[44:45], v44 offset0:192 offset1:225
	ds_read2_b32 v[52:53], v51 offset0:2 offset1:35
	s_waitcnt lgkmcnt(14)
	v_pk_add_f32 v[10:11], v[10:11], 0 op_sel_hi:[1,0]
	v_pk_add_f32 v[12:13], v[12:13], 0 op_sel_hi:[1,0]
	s_waitcnt lgkmcnt(13)
	v_pk_add_f32 v[10:11], v[10:11], v[14:15]
	s_waitcnt lgkmcnt(12)
	v_pk_add_f32 v[12:13], v[12:13], v[16:17]
	s_waitcnt lgkmcnt(11)
	v_pk_add_f32 v[10:11], v[10:11], v[18:19]
	s_waitcnt lgkmcnt(10)
	v_pk_add_f32 v[12:13], v[12:13], v[20:21]
	s_waitcnt lgkmcnt(9)
	v_pk_add_f32 v[10:11], v[10:11], v[22:23]
	s_waitcnt lgkmcnt(8)
	v_pk_add_f32 v[12:13], v[12:13], v[24:25]
	s_waitcnt lgkmcnt(7)
	v_pk_add_f32 v[10:11], v[10:11], v[26:27]
	s_waitcnt lgkmcnt(6)
	v_pk_add_f32 v[12:13], v[12:13], v[28:29]
	s_waitcnt lgkmcnt(5)
	v_pk_add_f32 v[10:11], v[10:11], v[30:31]
	s_waitcnt lgkmcnt(4)
	v_pk_add_f32 v[12:13], v[12:13], v[32:33]
	s_waitcnt lgkmcnt(3)
	v_pk_add_f32 v[10:11], v[10:11], v[34:35]
	s_waitcnt lgkmcnt(2)
	v_pk_add_f32 v[12:13], v[12:13], v[42:43]
	s_waitcnt lgkmcnt(1)
	v_pk_add_f32 v[10:11], v[10:11], v[44:45]
	s_waitcnt lgkmcnt(0)
	v_pk_add_f32 v[12:13], v[12:13], v[52:53]
	s_waitcnt vmcnt(0)
	v_lshlrev_b32_e32 v14, 16, v6
	v_and_b32_e32 v15, 0xffff0000, v6
	v_lshlrev_b32_e32 v6, 16, v7
	v_and_b32_e32 v7, 0xffff0000, v7
	v_pk_add_f32 v[10:11], v[10:11], v[14:15]
	v_pk_add_f32 v[12:13], v[12:13], v[6:7]
	v_pk_mul_f32 v[6:7], v[10:11], v[10:11]
	v_pk_mul_f32 v[14:15], v[12:13], v[12:13]
	v_add_f32_e32 v6, v6, v7
	v_add_f32_e32 v2, v14, v15
	v_add_f32_e32 v2, v6, v2
	ds_bpermute_b32 v6, v181, v2
	v_cvt_pk_bf16_f32 v10, v10, v11
	v_cvt_pk_bf16_f32 v11, v12, v13
	global_store_dwordx2 v[8:9], v[10:11], off
	s_waitcnt lgkmcnt(0)
	v_add_f32_e32 v2, v2, v6
	ds_bpermute_b32 v6, v196, v2
	s_waitcnt lgkmcnt(0)
	v_add_f32_e32 v2, v2, v6
	ds_bpermute_b32 v6, v197, v2
	s_waitcnt lgkmcnt(0)
	v_add_f32_e32 v2, v2, v6
	ds_bpermute_b32 v6, v198, v2
	s_and_saveexec_b64 s[4:5], vcc
	s_cbranch_execz .LBB0_1007
	v_lshlrev_b64 v[4:5], 6, v[4:5]
	v_lshl_add_u64 v[4:5], s[14:15], 0, v[4:5]
	s_lshr_b32 s78, s7, 4
	s_waitcnt lgkmcnt(0)
	v_add_f32_e32 v2, v2, v6
	v_lshl_add_u64 v[4:5], v[4:5], 0, s[78:79]
	global_store_dword v[4:5], v2, off
	s_branch .LBB0_1007

; template <int MODE> __device__ __forceinline__ void small_gemm_res(LAS unsigned char* lds, const bf16* A, const bf16* Bt, int K, const float* base, const bf16* baseb, float* H, bf16* XN, float* SS, float alpha, const bf16* GGs, int bx, int G, int tid) {
;     ...
;     for (int tile = bx; tile < 256; tile += G) {
;         const int t0 = (tile >> 4) * 32, n0 = (tile & 15) * 64;
;         f32x16 acc0, acc1;
; #pragma unroll
;         for (int r = 0; r < 16; ++r) { acc0[r] = 0.f; acc1[r] = 0.f; }
;         const bf16* ap = A + (size_t)(t0 + r32) * K + w * kw + 8 * hi;
;         const bf16* b0p = Bt + (size_t)(n0 + r32) * K + w * kw + 8 * hi; const bf16* b1p = b0p + (size_t)32 * K;
; #pragma unroll 4
;         for (int k = 0; k < kw; k += 16) {
;             const bf16x8 x = *(const bf16x8*)(ap + k), w0 = *(const bf16x8*)(b0p + k), w1 = *(const bf16x8*)(b1p + k);
;             acc0 = __builtin_amdgcn_mfma_f32_32x32x16_bf16(w0, x, acc0, 0, 0, 0); acc1 = __builtin_amdgcn_mfma_f32_32x32x16_bf16(w1, x, acc1, 0, 0, 0);
;         }
.LBB0_1179:
	s_and_b32 s2, s13, 0xffffffe0
	s_and_b32 s1, s3, 0x3c0
	v_or_b32_e32 v0, s2, v40
	v_or_b32_e32 v1, s1, v40
	v_mad_i64_i32 v[84:85], s[10:11], v0, s0, v[34:35]
	v_mul_u32_u24_e32 v0, 0xb00, v1
	v_lshlrev_b32_e32 v32, 1, v0
	v_lshl_add_u64 v[86:87], v[36:37], 0, v[32:33]
	v_add_co_u32_e32 v88, vcc, 0x2c000, v86
	s_lshl_b32 s8, s1, 1
	s_add_i32 s56, s56, s70
	v_addc_co_u32_e32 v89, vcc, 0, v87, vcc
	s_add_i32 s3, s3, s12
	s_add_i32 s13, s13, s14
	s_cmpk_lt_i32 s56, 0x100
	v_add_u32_e32 v60, s2, v41
	v_ashrrev_i32_e32 v61, 31, v60
	v_lshlrev_b64 v[60:61], 11, v[60:61]
	v_lshl_add_u64 v[60:61], s[6:7], 0, v[60:61]
	v_lshl_add_u64 v[60:61], v[60:61], 0, s[8:9]
	v_lshl_add_u64 v[60:61], v[60:61], 0, v[38:39]
	global_load_dwordx4 v[64:67], v[86:87], off
	global_load_dwordx4 v[68:71], v[84:85], off
	global_load_dwordx4 v[72:75], v[88:89], off
	global_load_dwordx4 v[76:79], v[86:87], off offset:32
	global_load_dwordx4 v[80:83], v[84:85], off offset:32
	global_load_dwordx4 v[92:95], v[88:89], off offset:32
	global_load_dwordx4 v[96:99], v[86:87], off offset:64
	global_load_dwordx4 v[100:103], v[84:85], off offset:64
	global_load_dwordx4 v[104:107], v[88:89], off offset:64
	global_load_dwordx4 v[108:111], v[86:87], off offset:96
	global_load_dwordx4 v[112:115], v[84:85], off offset:96
	global_load_dwordx4 v[116:119], v[88:89], off offset:96
	global_load_dwordx4 v[120:123], v[86:87], off offset:128
	global_load_dwordx4 v[124:127], v[84:85], off offset:128
	global_load_dwordx4 v[208:211], v[88:89], off offset:128
	global_load_dwordx4 v[212:215], v[86:87], off offset:160
	global_load_dwordx4 v[216:219], v[84:85], off offset:160
	global_load_dwordx4 v[220:223], v[88:89], off offset:160
	global_load_dwordx4 v[224:227], v[86:87], off offset:192
	global_load_dwordx4 v[228:231], v[84:85], off offset:192
	global_load_dwordx4 v[232:235], v[88:89], off offset:192
	global_load_dwordx4 v[236:239], v[86:87], off offset:224
	global_load_dwordx4 v[166:169], v[84:85], off offset:224
	global_load_dwordx4 v[170:173], v[88:89], off offset:224
	global_load_dwordx4 v[174:177], v[86:87], off offset:256
	global_load_dwordx4 v[182:185], v[84:85], off offset:256
	global_load_dwordx4 v[186:189], v[88:89], off offset:256
	s_waitcnt vmcnt(24)
	v_mfma_f32_32x32x16_bf16 v[16:31], v[64:67], v[68:71], 0
	v_mfma_f32_32x32x16_bf16 v[0:15], v[72:75], v[68:71], 0
	global_load_dwordx4 v[64:67], v[86:87], off offset:288
	global_load_dwordx4 v[68:71], v[84:85], off offset:288
	global_load_dwordx4 v[72:75], v[88:89], off offset:288
	s_waitcnt vmcnt(24)
	v_mfma_f32_32x32x16_bf16 v[16:31], v[76:79], v[80:83], v[16:31]
	v_mfma_f32_32x32x16_bf16 v[0:15], v[92:95], v[80:83], v[0:15]
	global_load_dwordx4 v[76:79], v[86:87], off offset:320
	global_load_dwordx4 v[80:83], v[84:85], off offset:320
	global_load_dwordx4 v[92:95], v[88:89], off offset:320
	s_waitcnt vmcnt(24)
	v_mfma_f32_32x32x16_bf16 v[16:31], v[96:99], v[100:103], v[16:31]
	v_mfma_f32_32x32x16_bf16 v[0:15], v[104:107], v[100:103], v[0:15]
	global_load_dwordx4 v[96:99], v[86:87], off offset:352
	global_load_dwordx4 v[100:103], v[84:85], off offset:352
	global_load_dwordx4 v[104:107], v[88:89], off offset:352
	s_waitcnt vmcnt(24)
	v_mfma_f32_32x32x16_bf16 v[16:31], v[108:111], v[112:115], v[16:31]
	v_mfma_f32_32x32x16_bf16 v[0:15], v[116:119], v[112:115], v[0:15]
	global_load_dwordx4 v[108:111], v[86:87], off offset:384
	global_load_dwordx4 v[112:115], v[84:85], off offset:384
	global_load_dwordx4 v[116:119], v[88:89], off offset:384
	s_waitcnt vmcnt(24)
	v_mfma_f32_32x32x16_bf16 v[16:31], v[120:123], v[124:127], v[16:31]
	v_mfma_f32_32x32x16_bf16 v[0:15], v[208:211], v[124:127], v[0:15]
	global_load_dwordx4 v[120:123], v[86:87], off offset:416
	global_load_dwordx4 v[124:127], v[84:85], off offset:416
	global_load_dwordx4 v[208:211], v[88:89], off offset:416
	s_waitcnt vmcnt(24)
	v_mfma_f32_32x32x16_bf16 v[16:31], v[212:215], v[216:219], v[16:31]
	v_mfma_f32_32x32x16_bf16 v[0:15], v[220:223], v[216:219], v[0:15]
	global_load_dwordx4 v[212:215], v[86:87], off offset:448
	global_load_dwordx4 v[216:219], v[84:85], off offset:448
	global_load_dwordx4 v[220:223], v[88:89], off offset:448
	s_waitcnt vmcnt(24)
	v_mfma_f32_32x32x16_bf16 v[16:31], v[224:227], v[228:231], v[16:31]
	v_mfma_f32_32x32x16_bf16 v[0:15], v[232:235], v[228:231], v[0:15]
	global_load_dwordx4 v[224:227], v[86:87], off offset:480
	global_load_dwordx4 v[228:231], v[84:85], off offset:480
	global_load_dwordx4 v[232:235], v[88:89], off offset:480
	s_waitcnt vmcnt(24)
	v_mfma_f32_32x32x16_bf16 v[16:31], v[236:239], v[166:169], v[16:31]
	v_mfma_f32_32x32x16_bf16 v[0:15], v[170:173], v[166:169], v[0:15]
	global_load_dwordx4 v[236:239], v[86:87], off offset:512
	global_load_dwordx4 v[166:169], v[84:85], off offset:512
	global_load_dwordx4 v[170:173], v[88:89], off offset:512
	s_waitcnt vmcnt(24)
	v_mfma_f32_32x32x16_bf16 v[16:31], v[174:177], v[182:185], v[16:31]
	v_mfma_f32_32x32x16_bf16 v[0:15], v[186:189], v[182:185], v[0:15]
	global_load_dwordx4 v[174:177], v[86:87], off offset:544
	global_load_dwordx4 v[182:185], v[84:85], off offset:544
	global_load_dwordx4 v[186:189], v[88:89], off offset:544
	s_waitcnt vmcnt(24)
	v_mfma_f32_32x32x16_bf16 v[16:31], v[64:67], v[68:71], v[16:31]
	v_mfma_f32_32x32x16_bf16 v[0:15], v[72:75], v[68:71], v[0:15]
	global_load_dwordx4 v[64:67], v[86:87], off offset:576
	global_load_dwordx4 v[68:71], v[84:85], off offset:576
	global_load_dwordx4 v[72:75], v[88:89], off offset:576
	s_waitcnt vmcnt(24)
; #define LAS __attribute__((address_space(3)))
; __device__ __forceinline__ unsigned pk2(float lo, float hi) { return pg8::cvt_pk_bf16(lo, hi); }
; __device__ __forceinline__ float bflo(unsigned w) { return __uint_as_float(w << 16); }
; __device__ __forceinline__ float bfhi(unsigned w) { return __uint_as_float(w & 0xffff0000u); }
; __device__ __forceinline__ int crow(int r, int hi) { return (r & 3) + 8 * (r >> 2) + 4 * hi; }
; template <int MODE> __device__ __forceinline__ void small_gemm_res(LAS unsigned char* lds, const bf16* A, const bf16* Bt, int K, const float* base, const bf16* baseb, float* H, bf16* XN, float* SS, float alpha, const bf16* GGs, int bx, int G, int tid) {
;     ...
;         for (int k = 0; k < kw; k += 16) {
;             const bf16x8 x = *(const bf16x8*)(ap + k), w0 = *(const bf16x8*)(b0p + k), w1 = *(const bf16x8*)(b1p + k);
;             acc0 = __builtin_amdgcn_mfma_f32_32x32x16_bf16(w0, x, acc0, 0, 0, 0); acc1 = __builtin_amdgcn_mfma_f32_32x32x16_bf16(w1, x, acc1, 0, 0, 0);
;         }
;         LAS float* Pw = P + w * 2112;
; #pragma unroll
;         for (int r = 0; r < 16; ++r) { Pw[crow(r, hi) * 33 + r32] = acc0[r]; Pw[(32 + crow(r, hi)) * 33 + r32] = acc1[r]; }
;         __syncthreads();
;         const int tok = tid >> 4, nq = tid & 15;
;         float v[4] = {0.f, 0.f, 0.f, 0.f};
; #pragma unroll
;         for (int ww = 0; ww < 8; ++ww)
; #pragma unroll
;             for (int e = 0; e < 4; ++e) v[e] += P[ww * 2112 + (4 * nq + e) * 33 + tok];
;         const size_t off = (size_t)(t0 + tok) * 1024 + n0 + 4 * nq;
;         if (MODE == 0) {
;             f32x4 b; if (baseb) { const u32x2 bw = *(const u32x2*)(baseb + off); b = (f32x4){bflo(bw.x), bfhi(bw.x), bflo(bw.y), bfhi(bw.y)}; } else b = *(const f32x4*)(base + off);
;             const f32x4 hv = (f32x4){b[0] + alpha * v[0], b[1] + alpha * v[1], b[2] + alpha * v[2], b[3] + alpha * v[3]};
;             if (H) *(f32x4*)(H + off) = hv;
;             if (XN) { u32x2 xw; xw.x = pk2(hv[0], hv[1]); xw.y = pk2(hv[2], hv[3]); *(u32x2*)(XN + off) = xw; }
	v_mfma_f32_32x32x16_bf16 v[16:31], v[76:79], v[80:83], v[16:31]
	v_mfma_f32_32x32x16_bf16 v[0:15], v[92:95], v[80:83], v[0:15]
	global_load_dwordx4 v[76:79], v[86:87], off offset:608
	global_load_dwordx4 v[80:83], v[84:85], off offset:608
	global_load_dwordx4 v[92:95], v[88:89], off offset:608
	s_waitcnt vmcnt(24)
	v_mfma_f32_32x32x16_bf16 v[16:31], v[96:99], v[100:103], v[16:31]
	v_mfma_f32_32x32x16_bf16 v[0:15], v[104:107], v[100:103], v[0:15]
	global_load_dwordx4 v[96:99], v[86:87], off offset:640
	global_load_dwordx4 v[100:103], v[84:85], off offset:640
	global_load_dwordx4 v[104:107], v[88:89], off offset:640
	s_waitcnt vmcnt(24)
	v_mfma_f32_32x32x16_bf16 v[16:31], v[108:111], v[112:115], v[16:31]
	v_mfma_f32_32x32x16_bf16 v[0:15], v[116:119], v[112:115], v[0:15]
	global_load_dwordx4 v[108:111], v[86:87], off offset:672
	global_load_dwordx4 v[112:115], v[84:85], off offset:672
	global_load_dwordx4 v[116:119], v[88:89], off offset:672
	s_waitcnt vmcnt(24)
	v_mfma_f32_32x32x16_bf16 v[16:31], v[120:123], v[124:127], v[16:31]
	v_mfma_f32_32x32x16_bf16 v[0:15], v[208:211], v[124:127], v[0:15]
	s_waitcnt vmcnt(21)
	v_mfma_f32_32x32x16_bf16 v[16:31], v[212:215], v[216:219], v[16:31]
	v_mfma_f32_32x32x16_bf16 v[0:15], v[220:223], v[216:219], v[0:15]
	s_waitcnt vmcnt(18)
	v_mfma_f32_32x32x16_bf16 v[16:31], v[224:227], v[228:231], v[16:31]
	v_mfma_f32_32x32x16_bf16 v[0:15], v[232:235], v[228:231], v[0:15]
	s_waitcnt vmcnt(15)
	v_mfma_f32_32x32x16_bf16 v[16:31], v[236:239], v[166:169], v[16:31]
	v_mfma_f32_32x32x16_bf16 v[0:15], v[170:173], v[166:169], v[0:15]
	s_waitcnt vmcnt(12)
	v_mfma_f32_32x32x16_bf16 v[16:31], v[174:177], v[182:185], v[16:31]
	v_mfma_f32_32x32x16_bf16 v[0:15], v[186:189], v[182:185], v[0:15]
	s_waitcnt vmcnt(9)
	v_mfma_f32_32x32x16_bf16 v[16:31], v[64:67], v[68:71], v[16:31]
	v_mfma_f32_32x32x16_bf16 v[0:15], v[72:75], v[68:71], v[0:15]
	s_waitcnt vmcnt(6)
	v_mfma_f32_32x32x16_bf16 v[16:31], v[76:79], v[80:83], v[16:31]
	v_mfma_f32_32x32x16_bf16 v[0:15], v[92:95], v[80:83], v[0:15]
	s_waitcnt vmcnt(3)
	v_mfma_f32_32x32x16_bf16 v[16:31], v[96:99], v[100:103], v[16:31]
	v_mfma_f32_32x32x16_bf16 v[0:15], v[104:107], v[100:103], v[0:15]
	s_waitcnt vmcnt(0)
	v_mfma_f32_32x32x16_bf16 v[16:31], v[108:111], v[112:115], v[16:31]
	v_mfma_f32_32x32x16_bf16 v[0:15], v[116:119], v[112:115], v[0:15]
	s_nop 10
	ds_write2_b32 v42, v16, v17 offset1:33
	ds_write2_b32 v42, v18, v19 offset0:66 offset1:99
	ds_write2_b32 v45, v20, v21 offset0:8 offset1:41
	ds_write2_b32 v45, v22, v23 offset0:74 offset1:107
	ds_write2_b32 v47, v24, v25 offset0:16 offset1:49
	ds_write2_b32 v47, v26, v27 offset0:82 offset1:115
	ds_write2_b32 v49, v28, v29 offset0:24 offset1:57
	ds_write2_b32 v49, v30, v31 offset0:90 offset1:123
	ds_write2_b32 v44, v0, v1 offset0:32 offset1:65
	ds_write2_b32 v44, v2, v3 offset0:98 offset1:131
	ds_write2_b32 v46, v4, v5 offset0:40 offset1:73
	ds_write2_b32 v46, v6, v7 offset0:106 offset1:139
	ds_write2_b32 v48, v8, v9 offset0:48 offset1:81
	ds_write2_b32 v48, v10, v11 offset0:114 offset1:147
	ds_write2_b32 v50, v12, v13 offset0:56 offset1:89
	ds_write2_b32 v50, v14, v15 offset0:122 offset1:155
	s_waitcnt lgkmcnt(0)
	s_barrier
	global_load_dwordx2 v[0:1], v[60:61], off
	ds_read2_b32 v[2:3], v43 offset1:33
	ds_read2_b32 v[4:5], v43 offset0:66 offset1:99
	ds_read2_b32 v[6:7], v51 offset0:64 offset1:97
	ds_read2_b32 v[8:9], v51 offset0:130 offset1:163
	ds_read2_b32 v[10:11], v52 offset0:128 offset1:161
	ds_read2_b32 v[12:13], v52 offset0:194 offset1:227
	ds_read2_b32 v[14:15], v53 offset0:192 offset1:225
	ds_read2_b32 v[16:17], v54 offset0:2 offset1:35
	ds_read2_b32 v[18:19], v55 offset1:33
	ds_read2_b32 v[20:21], v55 offset0:66 offset1:99
	ds_read2_b32 v[22:23], v56 offset0:64 offset1:97
	ds_read2_b32 v[24:25], v56 offset0:130 offset1:163
	ds_read2_b32 v[26:27], v57 offset0:128 offset1:161
	ds_read2_b32 v[28:29], v57 offset0:194 offset1:227
	ds_read2_b32 v[30:31], v58 offset0:192 offset1:225
	ds_read2_b32 v[62:63], v59 offset0:2 offset1:35
	s_waitcnt lgkmcnt(14)
	v_pk_add_f32 v[2:3], v[2:3], 0 op_sel_hi:[1,0]
	v_pk_add_f32 v[4:5], v[4:5], 0 op_sel_hi:[1,0]
	s_waitcnt lgkmcnt(13)
	v_pk_add_f32 v[2:3], v[2:3], v[6:7]
	s_waitcnt lgkmcnt(12)
	v_pk_add_f32 v[4:5], v[4:5], v[8:9]
	s_waitcnt lgkmcnt(11)
	v_pk_add_f32 v[2:3], v[2:3], v[10:11]
	s_waitcnt lgkmcnt(10)
	v_pk_add_f32 v[4:5], v[4:5], v[12:13]
	s_waitcnt lgkmcnt(9)
	v_pk_add_f32 v[2:3], v[2:3], v[14:15]
	s_waitcnt lgkmcnt(8)
	v_pk_add_f32 v[4:5], v[4:5], v[16:17]
	s_waitcnt lgkmcnt(7)
	v_pk_add_f32 v[2:3], v[2:3], v[18:19]
	s_waitcnt lgkmcnt(6)
	v_pk_add_f32 v[4:5], v[4:5], v[20:21]
	s_waitcnt lgkmcnt(5)
	v_pk_add_f32 v[2:3], v[2:3], v[22:23]
	s_waitcnt lgkmcnt(4)
	v_pk_add_f32 v[4:5], v[4:5], v[24:25]
	s_waitcnt lgkmcnt(3)
	v_pk_add_f32 v[2:3], v[2:3], v[26:27]
	s_waitcnt lgkmcnt(2)
	v_pk_add_f32 v[4:5], v[4:5], v[28:29]
	s_waitcnt lgkmcnt(1)
	v_pk_add_f32 v[2:3], v[2:3], v[30:31]
	s_waitcnt lgkmcnt(0)
	v_pk_add_f32 v[4:5], v[4:5], v[62:63]
	s_waitcnt vmcnt(0)
	v_lshlrev_b32_e32 v6, 16, v0
	v_and_b32_e32 v7, 0xffff0000, v0
	v_lshlrev_b32_e32 v0, 16, v1
	v_and_b32_e32 v1, 0xffff0000, v1
	v_pk_fma_f32 v[2:3], v[2:3], 0.5, v[6:7] op_sel_hi:[1,0,1]
	v_pk_fma_f32 v[0:1], v[4:5], 0.5, v[0:1] op_sel_hi:[1,0,1]
	v_cvt_pk_bf16_f32 v2, v2, v3
	v_cvt_pk_bf16_f32 v3, v0, v1
	global_store_dwordx2 v[60:61], v[2:3], off
	s_barrier
	s_cbranch_scc1 .LBB0_1179
